# up-GEMM k-loop: LDS-DMA staging rebalanced 2/6/2/6 -> 4/4/4/4 per phase (counted vmcnt re-derived) and DMA addressing switched to SGPR-base + 32-bit VGPR offset
# speedup vs baseline: 1.0013x; 1.0013x over previous
; __device__ __forceinline__ f32x2 gelu_pk(f32x2 v) {
;     const f32x2 av = __builtin_elementwise_abs(v), d = av * 0.2316418882f + 1.0f;
;     f32x2 t; t.x = __builtin_amdgcn_rcpf(d.x); t.y = __builtin_amdgcn_rcpf(d.y);
;     f32x2 q = t * 0.5307027145f + (-0.7265760135f); q = q * t + 0.7107068705f; q = q * t + (-0.142248368f); q = q * t + 0.127414796f; q = q * t;
;     const f32x2 s = (v * v) * (-0.72134752044f);
;     f32x2 e; e.x = __builtin_amdgcn_exp2f(s.x); e.y = __builtin_amdgcn_exp2f(s.y);
;     const f32x2 m = v * (q * e), r = v - m;
;     f32x2 o; o.x = v.x < 0.f ? m.x : r.x; o.y = v.y < 0.f ? m.y : r.y; return o;
; }
; __global__ void __launch_bounds__(NWAVES * 64, 2) mega_fwd(Args args) {
;     ...
;                 if (bx < total) {
;                     auto mkref = [&](int L, int pass) { const int bh = L >> 2, xq = L & 3; const int qb = pass ? 7 - xq : xq; const int bp = bh >> 4, h = bh & 15; const int b = bp < 8 ? 2 * bp + 1 : 2 * (bp - 8);
;                         fox::BlockRef r; const size_t rowb = (size_t)b * SEQ;
;                         r.Q = (const fox::bf16*)QKV + (rowb + qb * 256) * QKV_LD + h * HD; r.K = (const fox::bf16*)QKV + rowb * QKV_LD + DM + h * HD; r.V = (const fox::bf16*)QKV + rowb * QKV_LD + 2 * DM + h * HD;
;                         r.Bias = CB + (size_t)(b * 16 + h) * SEQ; r.O = (fox::bf16*)ATT + (rowb + qb * 256) * DM + h * HD; r.P0 = qb * 256; return r; };
;                     int L = bx, pass = 0; fox::BlockRef cur = mkref(L, 0); fox::Seam S;
.LBB0_474:
	s_and_b32 s98, s2, 7
	s_lshl_b32 s98, s98, 5
	s_lshr_b32 s99, s2, 3
	s_or_b32 s98, s98, s99
	s_cmpk_lt_i32 s2, 0xc00
	s_cselect_b64 s[6:7], -1, 0
	v_writelane_b32 v254, s6, 4
	s_lshl_b32 s5, s2, 7
	s_lshl_b32 s25, s20, 7
	v_writelane_b32 v254, s7, 5
	s_cmpk_gt_i32 s2, 0xff
	v_writelane_b32 v254, s5, 6
	s_cselect_b64 s[6:7], -1, 0
	v_writelane_b32 v254, s6, 7
	s_ashr_i32 s5, s98, 6
	s_movk_i32 s63, 0x181
	v_writelane_b32 v254, s7, 8
	s_lshl_b32 s6, s5, 1
	s_or_b32 s7, s6, 1
	s_add_i32 s6, s6, -16
	s_cmp_lt_i32 s5, 8
	s_cselect_b32 s6, s7, s6
	s_ashr_i32 s7, s6, 31
	s_lshl_b64 s[8:9], s[6:7], 11
	s_lshl_b32 s7, s98, 8
	s_and_b32 s11, s7, 0x300
	s_or_b32 s8, s8, s11
	s_mul_i32 s7, s9, 0x3000
	s_mul_hi_u32 s10, s8, 0x3000
	s_add_i32 s7, s10, s7
	v_writelane_b32 v254, s7, 9
	s_mul_i32 s7, s8, 0x3000
	v_writelane_b32 v254, s7, 10
	s_mul_hi_i32 s7, s6, 0x1800000
	s_bfe_u32 s5, s98, 0x40002
	v_writelane_b32 v254, s7, 11
	s_mul_i32 s7, s6, 0x1800000
	s_lshl_b32 s6, s6, 4
	s_or_b32 s6, s6, s5
	v_writelane_b32 v254, s7, 12
	s_ashr_i32 s7, s6, 31
	s_lshl_b64 s[6:7], s[6:7], 13
	v_writelane_b32 v254, s6, 13
	s_lshl_b32 s10, s5, 7
	s_mul_i32 s5, s11, 0x3000
	v_writelane_b32 v254, s7, 14
	s_lshl_b64 s[6:7], s[8:9], 12
	v_writelane_b32 v254, s6, 15
	s_add_i32 s5, s5, 0x240000
	s_movk_i32 s14, 0x2c1
	v_writelane_b32 v254, s7, 16
	v_writelane_b32 v254, s11, 17
	v_writelane_b32 v254, s5, 18
	s_lshl_b32 s5, s66, 7
	s_cmpk_lt_i32 s2, 0x1600
	s_cselect_b64 s[6:7], -1, 0
	v_writelane_b32 v254, s6, 19
	s_mul_i32 s71, s21, s20
	s_waitcnt lgkmcnt(0)
	v_mbcnt_lo_u32_b32 v0, -1, 0
	v_writelane_b32 v254, s7, 20
	s_and_b64 s[6:7], s[12:13], exec
	s_cselect_b32 s6, s63, 0x180
	s_mul_i32 s6, s66, s6
	s_add_i32 s6, s6, s65
	s_mul_hi_i32 s7, s6, 0x2aaaaaab
	s_lshr_b32 s8, s7, 31
	s_ashr_i32 s7, s7, 5
	s_add_i32 s7, s7, s8
	s_lshl_b32 s8, s7, 3
	s_mulk_i32 s7, 0xc0
	s_sub_i32 s7, s6, s7
	s_bfe_u32 s6, s7, 0x3001c
	s_add_i32 s9, s7, s6
	s_sext_i32_i16 s11, s9
	s_and_b32 s9, s9, 0xfff8
	s_sub_i32 s7, s7, s9
	s_sext_i32_i16 s7, s7
	s_lshr_b32 s6, s11, 3
	s_add_i32 s16, s8, s7
	s_ashr_i32 s7, s11, 3
	s_and_b64 s[8:9], s[12:13], exec
	s_cselect_b32 s4, s4, s5
	s_add_i32 s4, s4, s65
	s_ashr_i32 s5, s4, 31
	s_lshr_b32 s5, s5, 26
	s_add_i32 s5, s4, s5
	v_writelane_b32 v254, s7, 21
	s_ashr_i32 s7, s5, 6
	s_and_b32 s5, s5, 0xffc0
	s_sub_i32 s5, s4, s5
	s_bfe_i32 s4, s5, 0x80000
	s_bfe_u32 s4, s4, 0x3000c
	s_add_i32 s8, s5, s4
	s_and_b32 s11, s8, 0xf8
	s_bfe_i32 s4, s8, 0x80000
	s_sub_i32 s8, s5, s11
	s_lshl_b32 s7, s7, 3
	s_sext_i32_i16 s9, s4
	s_sext_i32_i8 s8, s8
	s_lshr_b32 s4, s9, 3
	s_add_i32 s18, s7, s8
	s_ashr_i32 s69, s9, 3
	s_and_b64 s[8:9], s[12:13], exec
	s_cselect_b32 s8, s14, 0x2c0
	s_mul_i32 s8, s66, s8
	s_add_i32 s8, s8, s65
	s_mul_hi_i32 s9, s8, 0x2e8ba2e9
	s_lshr_b32 s12, s9, 31
	s_ashr_i32 s9, s9, 6
	s_add_i32 s9, s9, s12
	s_lshl_b32 s12, s9, 3
	s_mulk_i32 s9, 0x160
	s_sub_i32 s9, s8, s9
	s_bfe_u32 s8, s9, 0x3001c
	s_add_i32 s13, s9, s8
	s_sext_i32_i16 s14, s13
	s_and_b32 s13, s13, 0xfff8
	s_sub_i32 s9, s9, s13
	s_sext_i32_i16 s9, s9
	s_add_i32 s26, s12, s9
	s_ashr_i32 s9, s14, 3
	v_writelane_b32 v254, s9, 22
	s_mov_b32 s12, s16
	s_sub_i32 s5, s11, s5
	s_ashr_i32 s17, s16, 31
	v_writelane_b32 v254, s12, 23
	s_sext_i32_i8 s5, s5
	s_sub_i32 s5, s5, s7
	v_writelane_b32 v254, s13, 24
	s_lshl_b64 s[12:13], s[16:17], 20
	v_writelane_b32 v254, s12, 25
	s_bfe_i64 s[6:7], s[6:7], 0x100000
	s_lshl_b64 s[6:7], s[6:7], 20
	v_writelane_b32 v254, s13, 26
	v_writelane_b32 v254, s6, 27
	s_ashr_i32 s19, s18, 31
	s_add_i32 s73, s5, 0x7f
	v_writelane_b32 v254, s7, 28
	s_mov_b32 s6, s18
	v_writelane_b32 v254, s6, 29
	s_bfe_i64 s[4:5], s[4:5], 0x100000
	s_lshl_b64 s[4:5], s[4:5], 20
	v_writelane_b32 v254, s7, 30
	s_lshl_b64 s[6:7], s[18:19], 20
	v_writelane_b32 v254, s6, 31
	s_ashr_i32 s27, s26, 31
	s_lshr_b32 s8, s14, 3
	v_writelane_b32 v254, s7, 32
	v_writelane_b32 v254, s4, 33
	s_mul_i32 s71, s71, s64
	s_movk_i32 s75, 0x3000
	v_writelane_b32 v254, s5, 34
	s_mov_b32 s4, s26
	v_writelane_b32 v254, s4, 35
	s_mov_b32 s37, 0
	s_movk_i32 s62, 0x1600
	v_writelane_b32 v254, s5, 36
	s_lshl_b64 s[4:5], s[26:27], 20
	v_writelane_b32 v254, s4, 37
	s_mov_b32 s77, 0xfffe0
	v_mov_b32_e32 v193, 0
	v_writelane_b32 v254, s5, 38
	s_bfe_i64 s[4:5], s[8:9], 0x100000
	s_lshl_b64 s[4:5], s[4:5], 20
	v_writelane_b32 v254, s4, 39
	s_mov_b64 s[8:9], 0
	s_mov_b64 s[64:65], 0x80
	v_writelane_b32 v254, s5, 40
	s_lshl_b64 s[4:5], s[2:3], 13
	s_add_u32 s4, s4, 0x33e00000
	v_writelane_b32 v254, s4, 41
	s_addc_u32 s4, s5, 0
	v_writelane_b32 v254, s4, 42
	s_mov_b64 s[4:5], 0
	v_writelane_b32 v254, s4, 43
	s_lshl_b64 s[52:53], s[22:23], 13
	s_add_i32 s79, 0, 0x21fc0
	v_writelane_b32 v254, s5, 44
	s_mov_b64 s[4:5], -1
	v_writelane_b32 v254, s4, 45
	v_mov_b32_e32 v220, 0x358637bd
	s_mov_b32 s68, 0x3e6d3388
	v_writelane_b32 v254, s5, 46
	s_lshl_b32 s4, s10, 1
	v_writelane_b32 v254, s4, 47
	v_writelane_b32 v254, s92, 48
	s_mov_b32 s70, 0x3f07dc22
	s_mov_b32 s72, 0xbf3a00e3
	v_writelane_b32 v254, s93, 49
	v_writelane_b32 v254, s82, 50
	s_add_i32 s81, 0, 0x21fc4
	v_mov_b32_e32 v221, 0x1000
	v_writelane_b32 v254, s83, 51
	v_writelane_b32 v254, s52, 52
	v_mov_b32_e32 v222, 0x2000
	v_mov_b32_e32 v223, 0x3000
	v_writelane_b32 v254, s53, 53
	v_writelane_b32 v254, s94, 54
	v_writelane_b32 v254, s69, 55
	v_writelane_b32 v254, s73, 56
	v_mov_b32_e32 v224, 1
	s_movk_i32 s87, 0x1800
	s_brev_b32 s91, -3
	s_mov_b32 s21, 0x41000000
	s_movk_i32 s26, 0x2c00
	v_mbcnt_hi_u32_b32 v225, -1, v0
	v_mov_b32_e32 v226, 0xff800000
	v_mov_b64_e32 v[194:195], 0x400
	v_mov_b64_e32 v[196:197], 0x3ff
	v_mov_b64_e32 v[198:199], 0x15ff
	s_mov_b32 s74, 0x3f35f0e3
	s_mov_b32 s76, 0xbe11a98e
	s_mov_b32 s78, 0x3e027906
	s_mov_b32 s80, 0xbf38aa3b
	s_mov_b64 s[84:85], 0x200
	s_mov_b32 s86, 0xbfb8aa3b
	s_mov_b32 s88, 0xc13504f3
	s_mov_b32 s90, 0x3e0293ee
	v_writelane_b32 v254, s79, 57
	s_barrier
	v_writelane_b32 v254, s81, 58
	s_branch .LBB0_478

; __device__ __forceinline__ int lane_id() { int l; asm volatile("v_mbcnt_lo_u32_b32 %0, -1, 0\n\tv_mbcnt_hi_u32_b32 %0, -1, %0" : "=v"(l)); return l; }
; #define VMW() asm volatile("s_waitcnt vmcnt(0)" ::: "memory")
; #define SLOAD_H(Kp, Vp, Bp, k0) do { S.st_v0 = load8(GROW(Vp, k0, voffk0)); S.st_v1 = load8(GROW(Vp, k0, voffk1));              \
;                          S.st_k0 = load8(GROW(Kp, k0, voffk0)); S.st_k1 = load8(GROW(Kp, k0, voffk1)); } while (0)
; #define SWRITE_HK(bf) do { *(bf16x8*)(K_lds + (bf) * SHM_K + kws) = S.st_k0; *(bf16x8*)(K_lds + (bf) * SHM_K + kws + 32 * 256) = S.st_k1; } while (0)
; __device__ __forceinline__ void fox_prime(const BlockRef& cur, char* lds, Seam& S, int wid) {
;     asm volatile("" : "+s"(wid));
;     int lane = lane_id(); asm volatile("" : "+v"(lane));
;     const int tid = wid * 64 + lane, r32 = lane & 31, hi = lane >> 5;
;     const int sr = tid >> 4, sc = (tid & 15) * 8, kws = KSWZ(sr, sc * 2); char* K_lds = lds + 2 * SHM_V;
;     const unsigned voffk0 = (unsigned)(sr * LDQ + sc) * 2u, voffk1 = voffk0 + 32u * LDQ * 2u, voffq = (unsigned)(r32 * LDQ + hi * 8) * 2u;
;     for (int d0 = 0; d0 < 8; ++d0) S.qr[d0] = load8((const bf16*)((const char*)(cur.Q + (size_t)(wid * QBLK) * LDQ) + voffq) + d0 * 16);
;     SLOAD_H(cur.K, cur.V, cur.Bias, ((cur.P0 + QB - 1) / KVBLK) * KVBLK); VMW(); SWRITE_HK(0);
;     __syncthreads();
; }
; __global__ void __launch_bounds__(NWAVES * 64, 2) mega_fwd(Args args) {
;     ...
;                     auto mkref = [&](int L, int pass) { const int bh = L >> 2, xq = L & 3; const int qb = pass ? 7 - xq : xq; const int bp = bh >> 4, h = bh & 15; const int b = bp < 8 ? 2 * bp + 1 : 2 * (bp - 8);
;                         fox::BlockRef r; const size_t rowb = (size_t)b * SEQ;
;                         r.Q = (const fox::bf16*)QKV + (rowb + qb * 256) * QKV_LD + h * HD; r.K = (const fox::bf16*)QKV + rowb * QKV_LD + DM + h * HD; r.V = (const fox::bf16*)QKV + rowb * QKV_LD + 2 * DM + h * HD;
;                         r.Bias = CB + (size_t)(b * 16 + h) * SEQ; r.O = (fox::bf16*)ATT + (rowb + qb * 256) * DM + h * HD; r.P0 = qb * 256; return r; };
;                     int L = bx, pass = 0; fox::BlockRef cur = mkref(L, 0); fox::Seam S;
;                     fox::fox_prime(cur, (char*)lds, S, wave_s);
.LBB0_643:
	s_mov_b64 s[8:9], s[0:1]
	s_mov_b64 s[4:5], s[0:1]
	s_waitcnt lgkmcnt(0)
	s_barrier
	s_mov_b64 s[4:5], s[0:1]
	s_nop 0
	v_readlane_b32 s4, v254, 0
	v_readlane_b32 s5, v254, 1
	s_and_b64 vcc, exec, s[4:5]
	s_cbranch_vccz .LBB0_814
	s_load_dwordx2 s[4:5], s[8:9], 0xa0
	v_readlane_b32 s6, v254, 47
	s_mov_b32 s52, 0
	v_readlane_b32 s51, v254, 17
	s_mov_b32 s53, s98
	s_waitcnt lgkmcnt(0)
	s_add_u32 s36, s4, 0x13c00000
	s_addc_u32 s42, s5, 0
	s_add_u32 s43, s4, 0x2bc00000
	s_addc_u32 s48, s5, 0
	s_add_u32 s49, s4, 0x33e00000
	s_addc_u32 s50, s5, 0
	v_readlane_b32 s4, v254, 10
	s_add_u32 s4, s36, s4
	v_readlane_b32 s5, v254, 9
	s_addc_u32 s5, s42, s5
	s_add_u32 s12, s4, s6
	s_addc_u32 s13, s5, 0
	v_readlane_b32 s4, v254, 12
	s_add_u32 s4, s36, s4
	v_readlane_b32 s5, v254, 11
	s_addc_u32 s5, s42, s5
	s_add_u32 s4, s4, s6
	s_addc_u32 s5, s5, 0
	s_add_u32 s14, s4, 0x1000
	s_addc_u32 s15, s5, 0
	s_add_u32 s16, s4, 0x2000
	s_addc_u32 s17, s5, 0
	v_readlane_b32 s4, v254, 13
	v_readlane_b32 s5, v254, 14
	s_add_u32 s30, s49, s4
	s_addc_u32 s31, s50, s5
	v_readlane_b32 s4, v254, 15
	v_readlane_b32 s5, v254, 16
	s_add_u32 s4, s43, s4
	s_addc_u32 s5, s48, s5
	s_add_u32 s28, s4, s6
	s_mov_b32 s6, s33
	v_mbcnt_lo_u32_b32 v0, -1, 0
	v_mbcnt_hi_u32_b32 v0, -1, v0
	s_addc_u32 s29, s5, 0
	s_lshl_b32 s4, s6, 5
	v_and_b32_e32 v1, 31, v0
	v_ashrrev_i32_e32 v2, 2, v0
	s_mul_i32 s5, s6, 0x60000
	v_mul_u32_u24_e32 v1, 0x1800, v1
	v_and_b32_e32 v2, 0x7ffffff8, v2
	s_mul_hi_i32 s7, s4, 0x3000
	s_add_u32 s4, s12, s5
	v_add_lshl_u32 v1, v1, v2, 1
	s_addc_u32 s5, s13, s7
	global_load_dwordx4 v[156:159], v1, s[4:5]
	global_load_dwordx4 v[152:155], v1, s[4:5] offset:32
	global_load_dwordx4 v[148:151], v1, s[4:5] offset:64
	global_load_dwordx4 v[144:147], v1, s[4:5] offset:96
	global_load_dwordx4 v[140:143], v1, s[4:5] offset:128
	global_load_dwordx4 v[136:139], v1, s[4:5] offset:160
	global_load_dwordx4 v[132:135], v1, s[4:5] offset:192
	global_load_dwordx4 v[128:131], v1, s[4:5] offset:224
	v_lshl_add_u32 v1, s6, 6, v0
	v_ashrrev_i32_e32 v2, 4, v1
	v_lshlrev_b32_e32 v0, 3, v0
	v_mul_lo_u32 v3, v2, s87
	v_and_b32_e32 v0, 0x78, v0
	v_or_b32_e32 v3, v3, v0
	v_lshlrev_b32_e32 v0, 1, v0
	s_movk_i32 s4, 0x70
	v_readlane_b32 s6, v254, 18
	v_bitop3_b32 v9, v0, v1, s4 bitop3:0x78
	s_add_u32 s4, s16, s6
	v_lshlrev_b32_e32 v3, 1, v3
	s_addc_u32 s5, s17, 0
	v_add_u32_e32 v4, 0x60000, v3
	global_load_dwordx4 v[96:99], v3, s[4:5]
	global_load_dwordx4 v[100:103], v4, s[4:5]
	s_add_u32 s4, s14, s6
	s_addc_u32 s5, s15, 0
	v_lshlrev_b32_e32 v8, 8, v2
	global_load_dwordx4 v[0:3], v3, s[4:5]
	s_nop 0
	global_load_dwordx4 v[4:7], v4, s[4:5]
	s_waitcnt vmcnt(0)
	v_add3_u32 v8, 0, v8, v9
	s_waitcnt vmcnt(1)
	ds_write_b128 v8, v[0:3] offset:32768
	s_waitcnt vmcnt(0)
	ds_write_b128 v8, v[4:7] offset:40960
	s_waitcnt lgkmcnt(0)
	s_barrier
	s_branch .LBB0_646

; #define PG8_STAGE(bufoff, gbase, voff) do { _Pragma("unroll") for (int _i = 0; _i < 2; ++_i) \
;         __builtin_amdgcn_global_load_lds((const unsigned*)((const char*)(gbase) + (voff)[_i]), (LAS unsigned*)(lds + (bufoff) + ldsw + _i * 8192), 16, 0, 0); } while (0)
; #define PG8_LDA(dst, b, h) do { _Pragma("unroll") for (int m = 0; m < 4; ++m) _Pragma("unroll") for (int k = 0; k < 2; ++k) dst[m][k] = *(const LAS bf16x8*)(lds + PG8_SA(b, h) + aoff + m * 2048 + k * 1024); } while (0)
; #define PG8_LDB(dst, b, h) do { _Pragma("unroll") for (int n = 0; n < 2; ++n) _Pragma("unroll") for (int k = 0; k < 2; ++k) dst[n][k] = *(const LAS bf16x8*)(lds + PG8_SB(b, h) + boff + n * 2048 + k * 1024); } while (0)
; #define PG8_MMA(ai, bj, At, Bt) do { __builtin_amdgcn_s_setprio(1); _Pragma("unroll") for (int m = 0; m < 4; ++m) _Pragma("unroll") for (int n = 0; n < 2; ++n) _Pragma("unroll") for (int k = 0; k < 2; ++k) \
;         acc[ai][bj][m][n] = __builtin_amdgcn_mfma_f32_16x16x32_bf16(Bt[n][k], At[m][k], acc[ai][bj][m][n], 0, 0, 0); __builtin_amdgcn_s_setprio(0); } while (0)
; #define PG8_WAIT_V(n) asm volatile("s_waitcnt vmcnt(" #n ")" ::: "memory")
; #define PG8_WAIT_L(n) asm volatile("s_waitcnt lgkmcnt(" #n ")" ::: "memory")
; #define PG8_BAR __builtin_amdgcn_s_barrier()
; template <class Epi, class Sched, bool ALIGN_EPI = false, bool SP2 = false>
; __device__ __forceinline__ void gemm_phase(LAS unsigned char* lds, const Gemm g, const Sched& S, const Epi& E, int wid) {
;     ...
;         for (int t = 0; t < nt; t += 2) {
;             const bool last = (t == nt - 2);
;             const char* a1 = cA + (size_t)(t + 1) * kstep;
;             const char* a2 = last ? nA : cA + (size_t)(t + 2) * kstep; const char* b2 = last ? nB : cB + (size_t)(t + 2) * kstep;
;             const char* a3 = a2 + kstep; const char* b3 = b2 + kstep;
;             if constexpr (SP2) {
;             PG8_LDB(B0, 0, 0); PG8_LDB(B1, 0, 1); PG8_SCHED; PG8_LDA(At, 0, 0); PG8_STAGE(PG8_SA(1, 1), a1 + hstepA, voffA);
;             PG8_WAIT_V(8); PG8_WAIT_L(0); PG8_BAR; PG8_MMA(0, 0, At, B0); PG8_MMA(0, 1, At, B1); PG8_BAR; PG8_SCHED;
;             PG8_LDA(At, 0, 1); PG8_STAGE(PG8_SB(0, 0), b2, voffB); PG8_STAGE(PG8_SB(0, 1), b2 + hstepB, voffB); PG8_STAGE(PG8_SA(0, 0), a2, voffA);
;             PG8_WAIT_V(8); PG8_WAIT_L(0); PG8_BAR; PG8_MMA(1, 0, At, B0); PG8_MMA(1, 1, At, B1); PG8_BAR; PG8_SCHED;
.LBB0_968:
	s_add_u32 s56, s54, 0x100
	s_addc_u32 s57, s55, 0
	s_add_i32 s62, 0, 0x10000
	s_cmp_eq_u32 s93, 28
	s_cselect_b32 s49, s41, s57
	s_cselect_b32 s48, s42, s56
	s_cselect_b32 vcc_hi, s43, s61
	s_cselect_b32 vcc_lo, s59, s60
	s_add_i32 s63, 0, 0x14000
	v_add_u32_e32 v116, s62, v228
	v_add_u32_e32 v132, s63, v228
	ds_read_b128 v[104:107], v116
	ds_read_b128 v[108:111], v116 offset:1024
	ds_read_b128 v[112:115], v116 offset:2048
	ds_read_b128 v[116:119], v116 offset:3072
	ds_read_b128 v[120:123], v132
	ds_read_b128 v[124:127], v132 offset:1024
	ds_read_b128 v[128:131], v132 offset:2048
	ds_read_b128 v[132:135], v132 offset:3072
	s_add_i32 m0, s79, 0xc000
	ds_read_b128 v[144:147], v231
	ds_read_b128 v[164:167], v231 offset:1024
	ds_read_b128 v[168:171], v231 offset:2048
	ds_read_b128 v[186:189], v231 offset:3072
	ds_read_b128 v[200:203], v231 offset:4096
	ds_read_b128 v[204:207], v231 offset:5120
	ds_read_b128 v[208:211], v231 offset:6144
	ds_read_b128 v[212:215], v231 offset:7168
	s_add_u32 s100, s54, 0x80
	s_addc_u32 s101, s55, 0
	s_mov_b32 m0, s94
	s_nop 0
	global_load_lds_dwordx4 v176, s[100:101]
	s_mov_b32 m0, s95
	s_nop 0
	global_load_lds_dwordx4 v174, s[100:101]
	s_add_u32 s100, s100, 0x80000
	s_addc_u32 s101, s101, 0
	s_add_i32 m0, s79, 0xc000
	s_nop 0
	global_load_lds_dwordx4 v176, s[100:101]
	s_add_i32 m0, s79, 0xe000
	s_nop 0
	global_load_lds_dwordx4 v174, s[100:101]
	s_waitcnt vmcnt(8)
	s_waitcnt lgkmcnt(0)
	s_barrier
	s_setprio 1
	s_waitcnt lgkmcnt(0)
	v_mfma_f32_16x16x32_bf16 v[160:163], v[104:107], v[144:147], v[160:163]
	v_mfma_f32_16x16x32_bf16 v[60:63], v[112:115], v[144:147], v[60:63]
	v_mfma_f32_16x16x32_bf16 v[152:155], v[104:107], v[168:171], v[152:155]
	v_mfma_f32_16x16x32_bf16 v[36:39], v[112:115], v[168:171], v[36:39]
	v_mfma_f32_16x16x32_bf16 v[140:143], v[104:107], v[200:203], v[140:143]
	v_mfma_f32_16x16x32_bf16 v[56:59], v[112:115], v[200:203], v[56:59]
	v_mfma_f32_16x16x32_bf16 v[100:103], v[104:107], v[208:211], v[100:103]
	v_mfma_f32_16x16x32_bf16 v[48:51], v[112:115], v[208:211], v[48:51]
	v_mfma_f32_16x16x32_bf16 v[160:163], v[108:111], v[164:167], v[160:163]
	v_mfma_f32_16x16x32_bf16 v[60:63], v[116:119], v[164:167], v[60:63]
	v_mfma_f32_16x16x32_bf16 v[152:155], v[108:111], v[186:189], v[152:155]
	v_mfma_f32_16x16x32_bf16 v[36:39], v[116:119], v[186:189], v[36:39]
	v_mfma_f32_16x16x32_bf16 v[140:143], v[108:111], v[204:207], v[140:143]
	v_mfma_f32_16x16x32_bf16 v[56:59], v[116:119], v[204:207], v[56:59]
	v_mfma_f32_16x16x32_bf16 v[100:103], v[108:111], v[212:215], v[100:103]
	v_mfma_f32_16x16x32_bf16 v[48:51], v[116:119], v[212:215], v[48:51]
	s_setprio 0
	s_setprio 1
	v_mfma_f32_16x16x32_bf16 v[156:159], v[120:123], v[144:147], v[156:159]
	v_mfma_f32_16x16x32_bf16 v[52:55], v[128:131], v[144:147], v[52:55]
	v_mfma_f32_16x16x32_bf16 v[32:35], v[128:131], v[168:171], v[32:35]
	v_mfma_f32_16x16x32_bf16 v[136:139], v[120:123], v[200:203], v[136:139]
	v_mfma_f32_16x16x32_bf16 v[44:47], v[128:131], v[200:203], v[44:47]
	v_mfma_f32_16x16x32_bf16 v[96:99], v[120:123], v[208:211], v[96:99]
	v_mfma_f32_16x16x32_bf16 v[40:43], v[128:131], v[208:211], v[40:43]
	v_mfma_f32_16x16x32_bf16 v[156:159], v[124:127], v[164:167], v[156:159]
	v_mfma_f32_16x16x32_bf16 v[52:55], v[132:135], v[164:167], v[52:55]
	v_mfma_f32_16x16x32_bf16 v[144:147], v[120:123], v[168:171], v[148:151]
	v_mfma_f32_16x16x32_bf16 v[32:35], v[132:135], v[186:189], v[32:35]
	v_mfma_f32_16x16x32_bf16 v[136:139], v[124:127], v[204:207], v[136:139]
	v_mfma_f32_16x16x32_bf16 v[44:47], v[132:135], v[204:207], v[44:47]
	v_mfma_f32_16x16x32_bf16 v[96:99], v[124:127], v[212:215], v[96:99]
	v_mfma_f32_16x16x32_bf16 v[40:43], v[132:135], v[212:215], v[40:43]
	v_mfma_f32_16x16x32_bf16 v[144:147], v[124:127], v[186:189], v[144:147]
	s_setprio 0
	s_barrier
	s_add_i32 s54, s62, s89
	s_mov_b64 s[100:101], vcc
	s_mov_b32 m0, s54
	ds_read_b128 v[148:151], v231 offset:16384
	ds_read_b128 v[164:167], v231 offset:17408
	ds_read_b128 v[168:171], v231 offset:18432
	ds_read_b128 v[186:189], v231 offset:19456
	ds_read_b128 v[200:203], v231 offset:20480
	ds_read_b128 v[204:207], v231 offset:21504
	ds_read_b128 v[208:211], v231 offset:22528
	ds_read_b128 v[212:215], v231 offset:23552
	global_load_lds_dwordx4 v192, s[100:101]
	s_add_i32 m0, s54, 0x2000
	s_add_u32 s54, vcc_lo, 0x80000
	s_addc_u32 s55, vcc_hi, 0
	s_add_i32 s62, s63, s89
	global_load_lds_dwordx4 v172, s[100:101]
	s_mov_b32 m0, s62
	s_nop 0
	global_load_lds_dwordx4 v192, s[54:55]
	s_add_i32 m0, s62, 0x2000
	s_nop 0
	global_load_lds_dwordx4 v172, s[54:55]
	s_waitcnt vmcnt(6)
	s_waitcnt lgkmcnt(0)
	s_barrier
; #define PG8_STAGE(bufoff, gbase, voff) do { _Pragma("unroll") for (int _i = 0; _i < 2; ++_i) \
;         __builtin_amdgcn_global_load_lds((const unsigned*)((const char*)(gbase) + (voff)[_i]), (LAS unsigned*)(lds + (bufoff) + ldsw + _i * 8192), 16, 0, 0); } while (0)
; #define PG8_LDA(dst, b, h) do { _Pragma("unroll") for (int m = 0; m < 4; ++m) _Pragma("unroll") for (int k = 0; k < 2; ++k) dst[m][k] = *(const LAS bf16x8*)(lds + PG8_SA(b, h) + aoff + m * 2048 + k * 1024); } while (0)
; #define PG8_LDB(dst, b, h) do { _Pragma("unroll") for (int n = 0; n < 2; ++n) _Pragma("unroll") for (int k = 0; k < 2; ++k) dst[n][k] = *(const LAS bf16x8*)(lds + PG8_SB(b, h) + boff + n * 2048 + k * 1024); } while (0)
; #define PG8_MMA(ai, bj, At, Bt) do { __builtin_amdgcn_s_setprio(1); _Pragma("unroll") for (int m = 0; m < 4; ++m) _Pragma("unroll") for (int n = 0; n < 2; ++n) _Pragma("unroll") for (int k = 0; k < 2; ++k) \
;         acc[ai][bj][m][n] = __builtin_amdgcn_mfma_f32_16x16x32_bf16(Bt[n][k], At[m][k], acc[ai][bj][m][n], 0, 0, 0); __builtin_amdgcn_s_setprio(0); } while (0)
; #define PG8_WAIT_V(n) asm volatile("s_waitcnt vmcnt(" #n ")" ::: "memory")
; #define PG8_WAIT_L(n) asm volatile("s_waitcnt lgkmcnt(" #n ")" ::: "memory")
; #define PG8_BAR __builtin_amdgcn_s_barrier()
; #define PG8_SCHED __builtin_amdgcn_sched_barrier(0)
; template <class Epi, class Sched, bool ALIGN_EPI = false, bool SP2 = false>
; __device__ __forceinline__ void gemm_phase(LAS unsigned char* lds, const Gemm g, const Sched& S, const Epi& E, int wid) {
;     ...
;             PG8_WAIT_V(8); PG8_WAIT_L(0); PG8_BAR; PG8_MMA(0, 0, At, B0); PG8_MMA(0, 1, At, B1); PG8_BAR; PG8_SCHED;
;             PG8_LDA(At, 0, 1); PG8_STAGE(PG8_SB(0, 0), b2, voffB); PG8_STAGE(PG8_SB(0, 1), b2 + hstepB, voffB); PG8_STAGE(PG8_SA(0, 0), a2, voffA);
;             PG8_WAIT_V(8); PG8_WAIT_L(0); PG8_BAR; PG8_MMA(1, 0, At, B0); PG8_MMA(1, 1, At, B1); PG8_BAR; PG8_SCHED;
;             PG8_LDB(B0, 1, 0); PG8_LDB(B1, 1, 1); PG8_SCHED; PG8_LDA(At, 1, 0); PG8_STAGE(PG8_SA(0, 1), a2 + hstepA, voffA);
;             PG8_WAIT_V(8); PG8_WAIT_L(0); PG8_BAR; PG8_MMA(0, 0, At, B0); PG8_MMA(0, 1, At, B1); PG8_BAR; PG8_SCHED;
;             PG8_LDA(At, 1, 1); PG8_STAGE(PG8_SB(1, 0), b3, voffB); PG8_STAGE(PG8_SB(1, 1), b3 + hstepB, voffB); PG8_STAGE(PG8_SA(1, 0), a3, voffA);
	s_setprio 1
	s_waitcnt lgkmcnt(0)
	v_mfma_f32_16x16x32_bf16 v[92:95], v[104:107], v[148:151], v[92:95]
	v_mfma_f32_16x16x32_bf16 v[28:31], v[112:115], v[148:151], v[28:31]
	v_mfma_f32_16x16x32_bf16 v[88:91], v[104:107], v[168:171], v[88:91]
	v_mfma_f32_16x16x32_bf16 v[4:7], v[112:115], v[168:171], v[4:7]
	v_mfma_f32_16x16x32_bf16 v[80:83], v[104:107], v[200:203], v[80:83]
	v_mfma_f32_16x16x32_bf16 v[24:27], v[112:115], v[200:203], v[24:27]
	v_mfma_f32_16x16x32_bf16 v[72:75], v[104:107], v[208:211], v[72:75]
	v_mfma_f32_16x16x32_bf16 v[16:19], v[112:115], v[208:211], v[16:19]
	v_mfma_f32_16x16x32_bf16 v[92:95], v[108:111], v[164:167], v[92:95]
	v_mfma_f32_16x16x32_bf16 v[28:31], v[116:119], v[164:167], v[28:31]
	v_mfma_f32_16x16x32_bf16 v[88:91], v[108:111], v[186:189], v[88:91]
	v_mfma_f32_16x16x32_bf16 v[4:7], v[116:119], v[186:189], v[4:7]
	v_mfma_f32_16x16x32_bf16 v[80:83], v[108:111], v[204:207], v[80:83]
	v_mfma_f32_16x16x32_bf16 v[24:27], v[116:119], v[204:207], v[24:27]
	v_mfma_f32_16x16x32_bf16 v[72:75], v[108:111], v[212:215], v[72:75]
	v_mfma_f32_16x16x32_bf16 v[16:19], v[116:119], v[212:215], v[16:19]
	s_setprio 0
	s_setprio 1
	v_mfma_f32_16x16x32_bf16 v[84:87], v[120:123], v[148:151], v[84:87]
	v_mfma_f32_16x16x32_bf16 v[20:23], v[128:131], v[148:151], v[20:23]
	v_mfma_f32_16x16x32_bf16 v[76:79], v[120:123], v[168:171], v[76:79]
	v_mfma_f32_16x16x32_bf16 v[0:3], v[128:131], v[168:171], v[0:3]
	v_mfma_f32_16x16x32_bf16 v[68:71], v[120:123], v[200:203], v[68:71]
	v_mfma_f32_16x16x32_bf16 v[12:15], v[128:131], v[200:203], v[12:15]
	v_mfma_f32_16x16x32_bf16 v[64:67], v[120:123], v[208:211], v[64:67]
	v_mfma_f32_16x16x32_bf16 v[8:11], v[128:131], v[208:211], v[8:11]
	v_mfma_f32_16x16x32_bf16 v[84:87], v[124:127], v[164:167], v[84:87]
	v_mfma_f32_16x16x32_bf16 v[20:23], v[132:135], v[164:167], v[20:23]
	v_mfma_f32_16x16x32_bf16 v[76:79], v[124:127], v[186:189], v[76:79]
	v_mfma_f32_16x16x32_bf16 v[0:3], v[132:135], v[186:189], v[0:3]
	v_mfma_f32_16x16x32_bf16 v[68:71], v[124:127], v[204:207], v[68:71]
	v_mfma_f32_16x16x32_bf16 v[12:15], v[132:135], v[204:207], v[12:15]
	v_mfma_f32_16x16x32_bf16 v[64:67], v[124:127], v[212:215], v[64:67]
	v_mfma_f32_16x16x32_bf16 v[8:11], v[132:135], v[212:215], v[8:11]
	s_setprio 0
	s_barrier
	s_add_i32 s54, 0, 0x18000
	s_add_i32 s55, 0, 0x1c000
	v_add_u32_e32 v116, s54, v228
	v_add_u32_e32 v132, s55, v228
	ds_read_b128 v[104:107], v116
	ds_read_b128 v[108:111], v116 offset:1024
	ds_read_b128 v[112:115], v116 offset:2048
	ds_read_b128 v[116:119], v116 offset:3072
	ds_read_b128 v[120:123], v132
	ds_read_b128 v[124:127], v132 offset:1024
	ds_read_b128 v[128:131], v132 offset:2048
	ds_read_b128 v[132:135], v132 offset:3072
	s_add_u32 s48, s48, 0x80000
	s_addc_u32 s49, s49, 0
	s_mov_b32 m0, s77
	ds_read_b128 v[148:151], v231 offset:32768
	ds_read_b128 v[164:167], v231 offset:33792
	ds_read_b128 v[168:171], v231 offset:34816
	ds_read_b128 v[186:189], v231 offset:35840
	ds_read_b128 v[200:203], v231 offset:36864
	ds_read_b128 v[204:207], v231 offset:37888
	ds_read_b128 v[208:211], v231 offset:38912
	ds_read_b128 v[212:215], v231 offset:39936
	s_add_u32 s100, s48, 0xfff80000
	s_addc_u32 s101, s49, -1
	s_mov_b32 m0, s79
	s_nop 0
	global_load_lds_dwordx4 v176, s[100:101]
	s_mov_b32 m0, s81
	s_nop 0
	global_load_lds_dwordx4 v174, s[100:101]
	s_mov_b32 m0, s77
	s_nop 0
	global_load_lds_dwordx4 v176, s[48:49]
	s_mov_b32 m0, s4
	s_nop 0
	global_load_lds_dwordx4 v174, s[48:49]
	s_waitcnt vmcnt(8)
	s_waitcnt lgkmcnt(0)
	s_barrier
; #define PG8_STAGE(bufoff, gbase, voff) do { _Pragma("unroll") for (int _i = 0; _i < 2; ++_i) \
;         __builtin_amdgcn_global_load_lds((const unsigned*)((const char*)(gbase) + (voff)[_i]), (LAS unsigned*)(lds + (bufoff) + ldsw + _i * 8192), 16, 0, 0); } while (0)
; #define PG8_LDA(dst, b, h) do { _Pragma("unroll") for (int m = 0; m < 4; ++m) _Pragma("unroll") for (int k = 0; k < 2; ++k) dst[m][k] = *(const LAS bf16x8*)(lds + PG8_SA(b, h) + aoff + m * 2048 + k * 1024); } while (0)
; #define PG8_LDB(dst, b, h) do { _Pragma("unroll") for (int n = 0; n < 2; ++n) _Pragma("unroll") for (int k = 0; k < 2; ++k) dst[n][k] = *(const LAS bf16x8*)(lds + PG8_SB(b, h) + boff + n * 2048 + k * 1024); } while (0)
; #define PG8_MMA(ai, bj, At, Bt) do { __builtin_amdgcn_s_setprio(1); _Pragma("unroll") for (int m = 0; m < 4; ++m) _Pragma("unroll") for (int n = 0; n < 2; ++n) _Pragma("unroll") for (int k = 0; k < 2; ++k) \
;         acc[ai][bj][m][n] = __builtin_amdgcn_mfma_f32_16x16x32_bf16(Bt[n][k], At[m][k], acc[ai][bj][m][n], 0, 0, 0); __builtin_amdgcn_s_setprio(0); } while (0)
; #define PG8_WAIT_V(n) asm volatile("s_waitcnt vmcnt(" #n ")" ::: "memory")
; #define PG8_WAIT_L(n) asm volatile("s_waitcnt lgkmcnt(" #n ")" ::: "memory")
; #define PG8_BAR __builtin_amdgcn_s_barrier()
; #define PG8_SCHED __builtin_amdgcn_sched_barrier(0)
; template <class Epi, class Sched, bool ALIGN_EPI = false, bool SP2 = false>
; __device__ __forceinline__ void gemm_phase(LAS unsigned char* lds, const Gemm g, const Sched& S, const Epi& E, int wid) {
;     ...
;         for (int t = 0; t < nt; t += 2) {
;             const bool last = (t == nt - 2);
;             const char* a1 = cA + (size_t)(t + 1) * kstep;
;             const char* a2 = last ? nA : cA + (size_t)(t + 2) * kstep; const char* b2 = last ? nB : cB + (size_t)(t + 2) * kstep;
;     ...
;             PG8_LDB(B0, 1, 0); PG8_LDB(B1, 1, 1); PG8_SCHED; PG8_LDA(At, 1, 0); PG8_STAGE(PG8_SA(0, 1), a2 + hstepA, voffA);
;             PG8_WAIT_V(8); PG8_WAIT_L(0); PG8_BAR; PG8_MMA(0, 0, At, B0); PG8_MMA(0, 1, At, B1); PG8_BAR; PG8_SCHED;
;             PG8_LDA(At, 1, 1); PG8_STAGE(PG8_SB(1, 0), b3, voffB); PG8_STAGE(PG8_SB(1, 1), b3 + hstepB, voffB); PG8_STAGE(PG8_SA(1, 0), a3, voffA);
;             PG8_WAIT_V(8); PG8_WAIT_L(0); PG8_BAR; PG8_MMA(1, 0, At, B0); PG8_MMA(1, 1, At, B1); PG8_BAR; PG8_SCHED;
	s_setprio 1
	s_waitcnt lgkmcnt(0)
	v_mfma_f32_16x16x32_bf16 v[160:163], v[104:107], v[148:151], v[160:163]
	v_mfma_f32_16x16x32_bf16 v[60:63], v[112:115], v[148:151], v[60:63]
	v_mfma_f32_16x16x32_bf16 v[152:155], v[104:107], v[168:171], v[152:155]
	v_mfma_f32_16x16x32_bf16 v[36:39], v[112:115], v[168:171], v[36:39]
	v_mfma_f32_16x16x32_bf16 v[140:143], v[104:107], v[200:203], v[140:143]
	v_mfma_f32_16x16x32_bf16 v[56:59], v[112:115], v[200:203], v[56:59]
	v_mfma_f32_16x16x32_bf16 v[100:103], v[104:107], v[208:211], v[100:103]
	v_mfma_f32_16x16x32_bf16 v[48:51], v[112:115], v[208:211], v[48:51]
	v_mfma_f32_16x16x32_bf16 v[160:163], v[108:111], v[164:167], v[160:163]
	v_mfma_f32_16x16x32_bf16 v[60:63], v[116:119], v[164:167], v[60:63]
	v_mfma_f32_16x16x32_bf16 v[152:155], v[108:111], v[186:189], v[152:155]
	v_mfma_f32_16x16x32_bf16 v[36:39], v[116:119], v[186:189], v[36:39]
	v_mfma_f32_16x16x32_bf16 v[140:143], v[108:111], v[204:207], v[140:143]
	v_mfma_f32_16x16x32_bf16 v[56:59], v[116:119], v[204:207], v[56:59]
	v_mfma_f32_16x16x32_bf16 v[100:103], v[108:111], v[212:215], v[100:103]
	v_mfma_f32_16x16x32_bf16 v[48:51], v[116:119], v[212:215], v[48:51]
	s_setprio 0
	s_setprio 1
	v_mfma_f32_16x16x32_bf16 v[156:159], v[120:123], v[148:151], v[156:159]
	v_mfma_f32_16x16x32_bf16 v[52:55], v[128:131], v[148:151], v[52:55]
	v_mfma_f32_16x16x32_bf16 v[144:147], v[120:123], v[168:171], v[144:147]
	v_mfma_f32_16x16x32_bf16 v[32:35], v[128:131], v[168:171], v[32:35]
	v_mfma_f32_16x16x32_bf16 v[136:139], v[120:123], v[200:203], v[136:139]
	v_mfma_f32_16x16x32_bf16 v[44:47], v[128:131], v[200:203], v[44:47]
	v_mfma_f32_16x16x32_bf16 v[96:99], v[120:123], v[208:211], v[96:99]
	v_mfma_f32_16x16x32_bf16 v[40:43], v[128:131], v[208:211], v[40:43]
	v_mfma_f32_16x16x32_bf16 v[156:159], v[124:127], v[164:167], v[156:159]
	v_mfma_f32_16x16x32_bf16 v[52:55], v[132:135], v[164:167], v[52:55]
	v_mfma_f32_16x16x32_bf16 v[148:151], v[124:127], v[186:189], v[144:147]
	v_mfma_f32_16x16x32_bf16 v[32:35], v[132:135], v[186:189], v[32:35]
	v_mfma_f32_16x16x32_bf16 v[136:139], v[124:127], v[204:207], v[136:139]
	v_mfma_f32_16x16x32_bf16 v[44:47], v[132:135], v[204:207], v[44:47]
	v_mfma_f32_16x16x32_bf16 v[96:99], v[124:127], v[212:215], v[96:99]
	v_mfma_f32_16x16x32_bf16 v[40:43], v[132:135], v[212:215], v[40:43]
	s_setprio 0
	s_barrier
	s_add_i32 s48, s54, s89
	s_add_u32 s100, vcc_lo, 0x80
	s_addc_u32 s101, vcc_hi, 0
	s_mov_b32 m0, s48
	ds_read_b128 v[144:147], v231 offset:49152
	ds_read_b128 v[164:167], v231 offset:50176
	ds_read_b128 v[168:171], v231 offset:51200
	ds_read_b128 v[186:189], v231 offset:52224
	ds_read_b128 v[200:203], v231 offset:53248
	ds_read_b128 v[204:207], v231 offset:54272
	ds_read_b128 v[208:211], v231 offset:55296
	ds_read_b128 v[212:215], v231 offset:56320
	global_load_lds_dwordx4 v192, s[100:101]
	s_add_i32 m0, s48, 0x2000
	s_add_u32 s48, vcc_lo, 0x80080
	s_addc_u32 s49, vcc_hi, 0
	s_add_i32 s54, s55, s89
	global_load_lds_dwordx4 v172, s[100:101]
	s_mov_b32 m0, s54
	s_nop 0
	global_load_lds_dwordx4 v192, s[48:49]
	s_add_i32 m0, s54, 0x2000
	s_nop 0
	global_load_lds_dwordx4 v172, s[48:49]
	s_waitcnt vmcnt(6)
	s_waitcnt lgkmcnt(0)
	s_barrier
	s_setprio 1
	s_waitcnt lgkmcnt(0)
	v_mfma_f32_16x16x32_bf16 v[92:95], v[104:107], v[144:147], v[92:95]
	v_mfma_f32_16x16x32_bf16 v[28:31], v[112:115], v[144:147], v[28:31]
	v_mfma_f32_16x16x32_bf16 v[88:91], v[104:107], v[168:171], v[88:91]
	v_mfma_f32_16x16x32_bf16 v[4:7], v[112:115], v[168:171], v[4:7]
	v_mfma_f32_16x16x32_bf16 v[80:83], v[104:107], v[200:203], v[80:83]
	v_mfma_f32_16x16x32_bf16 v[24:27], v[112:115], v[200:203], v[24:27]
	v_mfma_f32_16x16x32_bf16 v[72:75], v[104:107], v[208:211], v[72:75]
	v_mfma_f32_16x16x32_bf16 v[16:19], v[112:115], v[208:211], v[16:19]
	v_mfma_f32_16x16x32_bf16 v[92:95], v[108:111], v[164:167], v[92:95]
	v_mfma_f32_16x16x32_bf16 v[28:31], v[116:119], v[164:167], v[28:31]
	v_mfma_f32_16x16x32_bf16 v[88:91], v[108:111], v[186:189], v[88:91]
	v_mfma_f32_16x16x32_bf16 v[4:7], v[116:119], v[186:189], v[4:7]
	v_mfma_f32_16x16x32_bf16 v[80:83], v[108:111], v[204:207], v[80:83]
	v_mfma_f32_16x16x32_bf16 v[24:27], v[116:119], v[204:207], v[24:27]
	v_mfma_f32_16x16x32_bf16 v[72:75], v[108:111], v[212:215], v[72:75]
	v_mfma_f32_16x16x32_bf16 v[16:19], v[116:119], v[212:215], v[16:19]
	s_setprio 0
	s_setprio 1
	v_mfma_f32_16x16x32_bf16 v[84:87], v[120:123], v[144:147], v[84:87]
	v_mfma_f32_16x16x32_bf16 v[20:23], v[128:131], v[144:147], v[20:23]
	v_mfma_f32_16x16x32_bf16 v[76:79], v[120:123], v[168:171], v[76:79]
	v_mfma_f32_16x16x32_bf16 v[0:3], v[128:131], v[168:171], v[0:3]
	v_mfma_f32_16x16x32_bf16 v[68:71], v[120:123], v[200:203], v[68:71]
	v_mfma_f32_16x16x32_bf16 v[12:15], v[128:131], v[200:203], v[12:15]
	v_mfma_f32_16x16x32_bf16 v[64:67], v[120:123], v[208:211], v[64:67]
	v_mfma_f32_16x16x32_bf16 v[8:11], v[128:131], v[208:211], v[8:11]
	v_mfma_f32_16x16x32_bf16 v[84:87], v[124:127], v[164:167], v[84:87]
	v_mfma_f32_16x16x32_bf16 v[20:23], v[132:135], v[164:167], v[20:23]
	v_mfma_f32_16x16x32_bf16 v[76:79], v[124:127], v[186:189], v[76:79]
	v_mfma_f32_16x16x32_bf16 v[0:3], v[132:135], v[186:189], v[0:3]
	v_mfma_f32_16x16x32_bf16 v[68:71], v[124:127], v[204:207], v[68:71]
	v_mfma_f32_16x16x32_bf16 v[12:15], v[132:135], v[204:207], v[12:15]
	v_mfma_f32_16x16x32_bf16 v[64:67], v[124:127], v[212:215], v[64:67]
	v_mfma_f32_16x16x32_bf16 v[8:11], v[132:135], v[212:215], v[8:11]
	s_setprio 0
	s_barrier
	s_add_i32 s93, s93, 2
	s_add_u32 s60, s60, 0x100
	s_addc_u32 s61, s61, 0
	s_cmp_gt_u32 s93, 29
	s_mov_b64 s[54:55], s[56:57]
	s_cbranch_scc0 .LBB0_968
	s_and_b64 vcc, exec, s[82:83]
	s_cbranch_vccz .LBB0_971
	s_barrier

; __global__ void __launch_bounds__(NWAVES * 64, 2) mega_fwd(Args args) {
	.amdhsa_kernel _Z8mega_fwd4Args
		.amdhsa_group_segment_fixed_size 0
		.amdhsa_private_segment_fixed_size 0
		.amdhsa_kernarg_size 424
		.amdhsa_user_sgpr_count 2
		.amdhsa_user_sgpr_dispatch_ptr 0
		.amdhsa_user_sgpr_queue_ptr 0
		.amdhsa_user_sgpr_kernarg_segment_ptr 1
		.amdhsa_user_sgpr_dispatch_id 0
		.amdhsa_user_sgpr_kernarg_preload_length 0
		.amdhsa_user_sgpr_kernarg_preload_offset 0
		.amdhsa_user_sgpr_private_segment_size 0
		.amdhsa_uses_dynamic_stack 0
		.amdhsa_enable_private_segment 0
		.amdhsa_system_sgpr_workgroup_id_x 1
		.amdhsa_system_sgpr_workgroup_id_y 0
		.amdhsa_system_sgpr_workgroup_id_z 0
		.amdhsa_system_sgpr_workgroup_info 0
		.amdhsa_system_vgpr_workitem_id 2
		.amdhsa_next_free_vgpr 255
		.amdhsa_next_free_sgpr 102
		.amdhsa_accum_offset 256
		.amdhsa_reserve_vcc 1
		.amdhsa_float_round_mode_32 0
		.amdhsa_float_round_mode_16_64 0
		.amdhsa_float_denorm_mode_32 3
		.amdhsa_float_denorm_mode_16_64 3
		.amdhsa_dx10_clamp 1
		.amdhsa_ieee_mode 1
		.amdhsa_fp16_overflow 0
		.amdhsa_tg_split 0
		.amdhsa_exception_fp_ieee_invalid_op 0
		.amdhsa_exception_fp_denorm_src 0
		.amdhsa_exception_fp_ieee_div_zero 0
		.amdhsa_exception_fp_ieee_overflow 0
		.amdhsa_exception_fp_ieee_underflow 0
		.amdhsa_exception_fp_ieee_inexact 0
		.amdhsa_exception_int_div_zero 0
	.end_amdhsa_kernel

; __global__ void __launch_bounds__(NWAVES * 64, 2) mega_fwd(Args args) {
amdhsa.kernels:
  - .agpr_count:     0
    .args:
      - .offset:         0
        .size:           168
        .value_kind:     by_value
      - .offset:         168
        .size:           4
        .value_kind:     hidden_block_count_x
      - .offset:         172
        .size:           4
        .value_kind:     hidden_block_count_y
      - .offset:         176
        .size:           4
        .value_kind:     hidden_block_count_z
      - .offset:         180
        .size:           2
        .value_kind:     hidden_group_size_x
      - .offset:         182
        .size:           2
        .value_kind:     hidden_group_size_y
      - .offset:         184
        .size:           2
        .value_kind:     hidden_group_size_z
      - .offset:         186
        .size:           2
        .value_kind:     hidden_remainder_x
      - .offset:         188
        .size:           2
        .value_kind:     hidden_remainder_y
      - .offset:         190
        .size:           2
        .value_kind:     hidden_remainder_z
      - .offset:         208
        .size:           8
        .value_kind:     hidden_global_offset_x
      - .offset:         216
        .size:           8
        .value_kind:     hidden_global_offset_y
      - .offset:         224
        .size:           8
        .value_kind:     hidden_global_offset_z
      - .offset:         232
        .size:           2
        .value_kind:     hidden_grid_dims
      - .offset:         256
        .size:           8
        .value_kind:     hidden_multigrid_sync_arg
      - .offset:         288
        .size:           4
        .value_kind:     hidden_dynamic_lds_size
    .group_segment_fixed_size: 0
    .kernarg_segment_align: 8
    .kernarg_segment_size: 424
    .language:       OpenCL C
    .language_version:
      - 2
      - 0
    .max_flat_workgroup_size: 512
    .name:           _Z8mega_fwd4Args
    .private_segment_fixed_size: 0
    .sgpr_count:     108
    .sgpr_spill_count: 63
    .symbol:         _Z8mega_fwd4Args.kd
    .uniform_work_group_size: 1
    .uses_dynamic_stack: false
    .vgpr_count:     255
    .vgpr_spill_count: 0
    .wavefront_size: 64
